# MLP-in epilogue rewritten by hand: per-row RMS scales precomputed once per phase into registers, epilogue has no loads/waits (bit-identical math)
# speedup vs baseline: 1.0454x; 1.0438x over previous
.LBB0_427:
	s_cmp_le_i32 s84, s24
	s_cselect_b64 s[2:3], -1, 0
	s_and_b64 s[0:1], s[2:3], s[4:5]
	s_andn2_b64 vcc, exec, s[0:1]
	s_cbranch_vccnz .LBB0_459
	ds_read_b64 v[2:3], v222
	v_lshrrev_b32_e32 v220, 8, v0
	v_and_b32_e32 v226, 15, v0
	v_lshl_or_b32 v220, v220, 6, v226
	v_lshlrev_b32_e32 v220, 7, v220
	v_mov_b32_e32 v221, 0x3a800000
	s_and_b32 s100, s81, 7
	s_lshl_b32 s100, s100, 3
	s_bfe_u32 s101, s81, 0x30003
	s_add_i32 s100, s100, s101
	s_lshl_b32 s100, s100, 15
	s_waitcnt lgkmcnt(0)
	v_readfirstlane_b32 s98, v2
	v_readfirstlane_b32 s99, v3
	s_nop 3
	s_add_u32 s98, s98, s100
	s_addc_u32 s99, s99, 0
	s_add_u32 s98, s98, 0x10900000
	s_addc_u32 s99, s99, 0
	s_mov_b32 s100, s98
	s_mov_b32 s101, s99
	s_nop 0
	global_load_dwordx4 v[2:5], v220, s[100:101]
	global_load_dwordx4 v[6:9], v220, s[100:101] offset:16
	global_load_dwordx4 v[10:13], v220, s[100:101] offset:32
	global_load_dwordx4 v[14:17], v220, s[100:101] offset:48
	global_load_dwordx4 v[18:21], v220, s[100:101] offset:64
	global_load_dwordx4 v[22:25], v220, s[100:101] offset:80
	global_load_dwordx4 v[26:29], v220, s[100:101] offset:96
	global_load_dwordx4 v[30:33], v220, s[100:101] offset:112
	s_mov_b32 s100, s98
	s_mov_b32 s101, s99
	s_nop 0
	global_load_dwordx4 v[34:37], v220, s[100:101] offset:2048
	global_load_dwordx4 v[38:41], v220, s[100:101] offset:2064
	global_load_dwordx4 v[42:45], v220, s[100:101] offset:2080
	global_load_dwordx4 v[46:49], v220, s[100:101] offset:2096
	global_load_dwordx4 v[50:53], v220, s[100:101] offset:2112
	global_load_dwordx4 v[54:57], v220, s[100:101] offset:2128
	global_load_dwordx4 v[58:61], v220, s[100:101] offset:2144
	global_load_dwordx4 v[62:65], v220, s[100:101] offset:2160
	s_add_u32 s100, s98, 0x1000
	s_addc_u32 s101, s99, 0
	s_nop 0
	global_load_dwordx4 v[66:69], v220, s[100:101]
	global_load_dwordx4 v[70:73], v220, s[100:101] offset:16
	global_load_dwordx4 v[74:77], v220, s[100:101] offset:32
	global_load_dwordx4 v[78:81], v220, s[100:101] offset:48
	global_load_dwordx4 v[82:85], v220, s[100:101] offset:64
	global_load_dwordx4 v[86:89], v220, s[100:101] offset:80
	global_load_dwordx4 v[90:93], v220, s[100:101] offset:96
	global_load_dwordx4 v[94:97], v220, s[100:101] offset:112
	s_add_u32 s100, s98, 0x1000
	s_addc_u32 s101, s99, 0
	s_nop 0
	global_load_dwordx4 v[98:101], v220, s[100:101] offset:2048
	global_load_dwordx4 v[102:105], v220, s[100:101] offset:2064
	global_load_dwordx4 v[106:109], v220, s[100:101] offset:2080
	global_load_dwordx4 v[110:113], v220, s[100:101] offset:2096
	global_load_dwordx4 v[114:117], v220, s[100:101] offset:2112
	global_load_dwordx4 v[118:121], v220, s[100:101] offset:2128
	global_load_dwordx4 v[122:125], v220, s[100:101] offset:2144
	global_load_dwordx4 v[126:129], v220, s[100:101] offset:2160
	s_add_u32 s100, s98, 0x4000
	s_addc_u32 s101, s99, 0
	s_nop 0
	global_load_dwordx4 v[156:159], v220, s[100:101]
	global_load_dwordx4 v[160:163], v220, s[100:101] offset:16
	global_load_dwordx4 v[164:167], v220, s[100:101] offset:32
	global_load_dwordx4 v[168:171], v220, s[100:101] offset:48
	global_load_dwordx4 v[172:175], v220, s[100:101] offset:64
	global_load_dwordx4 v[176:179], v220, s[100:101] offset:80
	global_load_dwordx4 v[180:183], v220, s[100:101] offset:96
	global_load_dwordx4 v[184:187], v220, s[100:101] offset:112
	s_add_u32 s100, s98, 0x4000
	s_addc_u32 s101, s99, 0
	s_nop 0
	global_load_dwordx4 v[188:191], v220, s[100:101] offset:2048
	global_load_dwordx4 v[192:195], v220, s[100:101] offset:2064
	global_load_dwordx4 v[196:199], v220, s[100:101] offset:2080
	global_load_dwordx4 v[200:203], v220, s[100:101] offset:2096
	global_load_dwordx4 v[204:207], v220, s[100:101] offset:2112
	global_load_dwordx4 v[208:211], v220, s[100:101] offset:2128
	global_load_dwordx4 v[212:215], v220, s[100:101] offset:2144
	global_load_dwordx4 v[216:219], v220, s[100:101] offset:2160
	s_waitcnt vmcnt(40)
	v_add_f32_e32 v226, v2, v3
	v_add_f32_e32 v228, v4, v5
	v_add_f32_e32 v233, v226, v228
	v_add_f32_e32 v226, v6, v7
	v_add_f32_e32 v228, v8, v9
	v_add_f32_e32 v226, v226, v228
	v_add_f32_e32 v233, v233, v226
	v_add_f32_e32 v226, v10, v11
	v_add_f32_e32 v228, v12, v13
	v_add_f32_e32 v226, v226, v228
	v_add_f32_e32 v233, v233, v226
	v_add_f32_e32 v226, v14, v15
	v_add_f32_e32 v228, v16, v17
	v_add_f32_e32 v226, v226, v228
	v_add_f32_e32 v233, v233, v226
	v_add_f32_e32 v226, v18, v19
	v_add_f32_e32 v228, v20, v21
	v_add_f32_e32 v226, v226, v228
	v_add_f32_e32 v233, v233, v226
	v_add_f32_e32 v226, v22, v23
	v_add_f32_e32 v228, v24, v25
	v_add_f32_e32 v226, v226, v228
	v_add_f32_e32 v233, v233, v226
	v_add_f32_e32 v226, v26, v27
	v_add_f32_e32 v228, v28, v29
	v_add_f32_e32 v226, v226, v228
	v_add_f32_e32 v233, v233, v226
	v_add_f32_e32 v226, v30, v31
	v_add_f32_e32 v228, v32, v33
	v_add_f32_e32 v226, v226, v228
	v_add_f32_e32 v233, v233, v226
	v_fmaak_f32 v233, v221, v233, 0x358637bd
	v_rsq_f32_e32 v232, v233
	s_waitcnt vmcnt(32)
	v_add_f32_e32 v226, v34, v35
	v_add_f32_e32 v228, v36, v37
	v_add_f32_e32 v233, v226, v228
	v_add_f32_e32 v226, v38, v39
	v_add_f32_e32 v228, v40, v41
	v_add_f32_e32 v226, v226, v228
	v_add_f32_e32 v233, v233, v226
	v_add_f32_e32 v226, v42, v43
	v_add_f32_e32 v228, v44, v45
	v_add_f32_e32 v226, v226, v228
	v_add_f32_e32 v233, v233, v226
	v_add_f32_e32 v226, v46, v47
	v_add_f32_e32 v228, v48, v49
	v_add_f32_e32 v226, v226, v228
	v_add_f32_e32 v233, v233, v226
	v_add_f32_e32 v226, v50, v51
	v_add_f32_e32 v228, v52, v53
	v_add_f32_e32 v226, v226, v228
	v_add_f32_e32 v233, v233, v226
	v_add_f32_e32 v226, v54, v55
	v_add_f32_e32 v228, v56, v57
	v_add_f32_e32 v226, v226, v228
	v_add_f32_e32 v233, v233, v226
	v_add_f32_e32 v226, v58, v59
	v_add_f32_e32 v228, v60, v61
	v_add_f32_e32 v226, v226, v228
	v_add_f32_e32 v233, v233, v226
	v_add_f32_e32 v226, v62, v63
	v_add_f32_e32 v228, v64, v65
	v_add_f32_e32 v226, v226, v228
	v_add_f32_e32 v233, v233, v226
	v_fmaak_f32 v233, v221, v233, 0x358637bd
	v_rsq_f32_e32 v234, v233
	s_add_u32 s100, s98, 0x5000
	s_addc_u32 s101, s99, 0
	s_nop 0
	global_load_dwordx4 v[2:5], v220, s[100:101]
	global_load_dwordx4 v[6:9], v220, s[100:101] offset:16
	global_load_dwordx4 v[10:13], v220, s[100:101] offset:32
	global_load_dwordx4 v[14:17], v220, s[100:101] offset:48
	global_load_dwordx4 v[18:21], v220, s[100:101] offset:64
	global_load_dwordx4 v[22:25], v220, s[100:101] offset:80
	global_load_dwordx4 v[26:29], v220, s[100:101] offset:96
	global_load_dwordx4 v[30:33], v220, s[100:101] offset:112
	s_add_u32 s100, s98, 0x5000
	s_addc_u32 s101, s99, 0
	s_nop 0
	global_load_dwordx4 v[34:37], v220, s[100:101] offset:2048
	global_load_dwordx4 v[38:41], v220, s[100:101] offset:2064
	global_load_dwordx4 v[42:45], v220, s[100:101] offset:2080
	global_load_dwordx4 v[46:49], v220, s[100:101] offset:2096
	global_load_dwordx4 v[50:53], v220, s[100:101] offset:2112
	global_load_dwordx4 v[54:57], v220, s[100:101] offset:2128
	global_load_dwordx4 v[58:61], v220, s[100:101] offset:2144
	global_load_dwordx4 v[62:65], v220, s[100:101] offset:2160
	s_waitcnt vmcnt(40)
	v_add_f32_e32 v226, v66, v67
	v_add_f32_e32 v228, v68, v69
	v_add_f32_e32 v233, v226, v228
	v_add_f32_e32 v226, v70, v71
	v_add_f32_e32 v228, v72, v73
	v_add_f32_e32 v226, v226, v228
	v_add_f32_e32 v233, v233, v226
	v_add_f32_e32 v226, v74, v75
	v_add_f32_e32 v228, v76, v77
	v_add_f32_e32 v226, v226, v228
	v_add_f32_e32 v233, v233, v226
	v_add_f32_e32 v226, v78, v79
	v_add_f32_e32 v228, v80, v81
	v_add_f32_e32 v226, v226, v228
	v_add_f32_e32 v233, v233, v226
	v_add_f32_e32 v226, v82, v83
	v_add_f32_e32 v228, v84, v85
	v_add_f32_e32 v226, v226, v228
	v_add_f32_e32 v233, v233, v226
	v_add_f32_e32 v226, v86, v87
	v_add_f32_e32 v228, v88, v89
	v_add_f32_e32 v226, v226, v228
	v_add_f32_e32 v233, v233, v226
	v_add_f32_e32 v226, v90, v91
	v_add_f32_e32 v228, v92, v93
	v_add_f32_e32 v226, v226, v228
	v_add_f32_e32 v233, v233, v226
	v_add_f32_e32 v226, v94, v95
	v_add_f32_e32 v228, v96, v97
	v_add_f32_e32 v226, v226, v228
	v_add_f32_e32 v233, v233, v226
	v_fmaak_f32 v233, v221, v233, 0x358637bd
	v_rsq_f32_e32 v236, v233
	s_waitcnt vmcnt(32)
	v_add_f32_e32 v226, v98, v99
	v_add_f32_e32 v228, v100, v101
	v_add_f32_e32 v233, v226, v228
	v_add_f32_e32 v226, v102, v103
	v_add_f32_e32 v228, v104, v105
	v_add_f32_e32 v226, v226, v228
	v_add_f32_e32 v233, v233, v226
	v_add_f32_e32 v226, v106, v107
	v_add_f32_e32 v228, v108, v109
	v_add_f32_e32 v226, v226, v228
	v_add_f32_e32 v233, v233, v226
	v_add_f32_e32 v226, v110, v111
	v_add_f32_e32 v228, v112, v113
	v_add_f32_e32 v226, v226, v228
	v_add_f32_e32 v233, v233, v226
	v_add_f32_e32 v226, v114, v115
	v_add_f32_e32 v228, v116, v117
	v_add_f32_e32 v226, v226, v228
	v_add_f32_e32 v233, v233, v226
	v_add_f32_e32 v226, v118, v119
	v_add_f32_e32 v228, v120, v121
	v_add_f32_e32 v226, v226, v228
	v_add_f32_e32 v233, v233, v226
	v_add_f32_e32 v226, v122, v123
	v_add_f32_e32 v228, v124, v125
	v_add_f32_e32 v226, v226, v228
	v_add_f32_e32 v233, v233, v226
	v_add_f32_e32 v226, v126, v127
	v_add_f32_e32 v228, v128, v129
	v_add_f32_e32 v226, v226, v228
	v_add_f32_e32 v233, v233, v226
	v_fmaak_f32 v233, v221, v233, 0x358637bd
	v_rsq_f32_e32 v238, v233
	s_waitcnt vmcnt(24)
	v_add_f32_e32 v226, v156, v157
	v_add_f32_e32 v228, v158, v159
	v_add_f32_e32 v233, v226, v228
	v_add_f32_e32 v226, v160, v161
	v_add_f32_e32 v228, v162, v163
	v_add_f32_e32 v226, v226, v228
	v_add_f32_e32 v233, v233, v226
	v_add_f32_e32 v226, v164, v165
	v_add_f32_e32 v228, v166, v167
	v_add_f32_e32 v226, v226, v228
	v_add_f32_e32 v233, v233, v226
	v_add_f32_e32 v226, v168, v169
	v_add_f32_e32 v228, v170, v171
	v_add_f32_e32 v226, v226, v228
	v_add_f32_e32 v233, v233, v226
	v_add_f32_e32 v226, v172, v173
	v_add_f32_e32 v228, v174, v175
	v_add_f32_e32 v226, v226, v228
	v_add_f32_e32 v233, v233, v226
	v_add_f32_e32 v226, v176, v177
	v_add_f32_e32 v228, v178, v179
	v_add_f32_e32 v226, v226, v228
	v_add_f32_e32 v233, v233, v226
	v_add_f32_e32 v226, v180, v181
	v_add_f32_e32 v228, v182, v183
	v_add_f32_e32 v226, v226, v228
	v_add_f32_e32 v233, v233, v226
	v_add_f32_e32 v226, v184, v185
	v_add_f32_e32 v228, v186, v187
	v_add_f32_e32 v226, v226, v228
	v_add_f32_e32 v233, v233, v226
	v_fmaak_f32 v233, v221, v233, 0x358637bd
	v_rsq_f32_e32 v240, v233
	s_waitcnt vmcnt(16)
	v_add_f32_e32 v226, v188, v189
	v_add_f32_e32 v228, v190, v191
	v_add_f32_e32 v233, v226, v228
	v_add_f32_e32 v226, v192, v193
	v_add_f32_e32 v228, v194, v195
	v_add_f32_e32 v226, v226, v228
	v_add_f32_e32 v233, v233, v226
	v_add_f32_e32 v226, v196, v197
	v_add_f32_e32 v228, v198, v199
	v_add_f32_e32 v226, v226, v228
	v_add_f32_e32 v233, v233, v226
	v_add_f32_e32 v226, v200, v201
	v_add_f32_e32 v228, v202, v203
	v_add_f32_e32 v226, v226, v228
	v_add_f32_e32 v233, v233, v226
	v_add_f32_e32 v226, v204, v205
	v_add_f32_e32 v228, v206, v207
	v_add_f32_e32 v226, v226, v228
	v_add_f32_e32 v233, v233, v226
	v_add_f32_e32 v226, v208, v209
	v_add_f32_e32 v228, v210, v211
	v_add_f32_e32 v226, v226, v228
	v_add_f32_e32 v233, v233, v226
	v_add_f32_e32 v226, v212, v213
	v_add_f32_e32 v228, v214, v215
	v_add_f32_e32 v226, v226, v228
	v_add_f32_e32 v233, v233, v226
	v_add_f32_e32 v226, v216, v217
	v_add_f32_e32 v228, v218, v219
	v_add_f32_e32 v226, v226, v228
	v_add_f32_e32 v233, v233, v226
	v_fmaak_f32 v233, v221, v233, 0x358637bd
	v_rsq_f32_e32 v242, v233
	s_waitcnt vmcnt(8)
	v_add_f32_e32 v226, v2, v3
	v_add_f32_e32 v228, v4, v5
	v_add_f32_e32 v233, v226, v228
	v_add_f32_e32 v226, v6, v7
	v_add_f32_e32 v228, v8, v9
	v_add_f32_e32 v226, v226, v228
	v_add_f32_e32 v233, v233, v226
	v_add_f32_e32 v226, v10, v11
	v_add_f32_e32 v228, v12, v13
	v_add_f32_e32 v226, v226, v228
	v_add_f32_e32 v233, v233, v226
	v_add_f32_e32 v226, v14, v15
	v_add_f32_e32 v228, v16, v17
	v_add_f32_e32 v226, v226, v228
	v_add_f32_e32 v233, v233, v226
	v_add_f32_e32 v226, v18, v19
	v_add_f32_e32 v228, v20, v21
	v_add_f32_e32 v226, v226, v228
	v_add_f32_e32 v233, v233, v226
	v_add_f32_e32 v226, v22, v23
	v_add_f32_e32 v228, v24, v25
	v_add_f32_e32 v226, v226, v228
	v_add_f32_e32 v233, v233, v226
	v_add_f32_e32 v226, v26, v27
	v_add_f32_e32 v228, v28, v29
	v_add_f32_e32 v226, v226, v228
	v_add_f32_e32 v233, v233, v226
	v_add_f32_e32 v226, v30, v31
	v_add_f32_e32 v228, v32, v33
	v_add_f32_e32 v226, v226, v228
	v_add_f32_e32 v233, v233, v226
	v_fmaak_f32 v233, v221, v233, 0x358637bd
	v_rsq_f32_e32 v244, v233
	s_waitcnt vmcnt(0)
	v_add_f32_e32 v226, v34, v35
	v_add_f32_e32 v228, v36, v37
	v_add_f32_e32 v233, v226, v228
	v_add_f32_e32 v226, v38, v39
	v_add_f32_e32 v228, v40, v41
	v_add_f32_e32 v226, v226, v228
	v_add_f32_e32 v233, v233, v226
	v_add_f32_e32 v226, v42, v43
	v_add_f32_e32 v228, v44, v45
	v_add_f32_e32 v226, v226, v228
	v_add_f32_e32 v233, v233, v226
	v_add_f32_e32 v226, v46, v47
	v_add_f32_e32 v228, v48, v49
	v_add_f32_e32 v226, v226, v228
	v_add_f32_e32 v233, v233, v226
	v_add_f32_e32 v226, v50, v51
	v_add_f32_e32 v228, v52, v53
	v_add_f32_e32 v226, v226, v228
	v_add_f32_e32 v233, v233, v226
	v_add_f32_e32 v226, v54, v55
	v_add_f32_e32 v228, v56, v57
	v_add_f32_e32 v226, v226, v228
	v_add_f32_e32 v233, v233, v226
	v_add_f32_e32 v226, v58, v59
	v_add_f32_e32 v228, v60, v61
	v_add_f32_e32 v226, v226, v228
	v_add_f32_e32 v233, v233, v226
	v_add_f32_e32 v226, v62, v63
	v_add_f32_e32 v228, v64, v65
	v_add_f32_e32 v226, v226, v228
	v_add_f32_e32 v233, v233, v226
	v_fmaak_f32 v233, v221, v233, 0x358637bd
	v_rsq_f32_e32 v246, v233
	s_lshl_b32 s26, s51, 22
	s_mov_b32 s27, s81
	s_waitcnt lgkmcnt(0)
	ds_read_b64 v[2:3], v222
	s_waitcnt lgkmcnt(0)
	s_waitcnt vmcnt(3)
	v_mov_b32 v10, v0
	s_cmpk_gt_i32 s27, 0x3ff
	v_readfirstlane_b32 s45, v3
	v_readfirstlane_b32 s44, v2
	v_readfirstlane_b32 s8, v10
	s_cbranch_scc1 .LBB0_452
	s_ashr_i32 s28, s27, 31
	s_lshr_b32 s0, s28, 29
	s_add_i32 s6, s27, s0
	s_and_b32 s0, s6, -8
	s_sub_i32 s5, s27, s0
	s_cmp_gt_i32 s5, -1
	s_mov_b64 s[0:1], -1
	s_cbranch_scc0 .LBB0_431
	s_lshl_b32 s4, s5, 7
	s_mov_b64 s[0:1], 0

.LBB0_448:
	v_lshl_add_u32 v140, s18, 8, v144
	v_lshl_add_u32 v141, s55, 9, v146
	v_lshl_add_u32 v141, v140, 13, v141
	v_pk_mul_f32 v[126:127], v[126:127], v[232:233] op_sel_hi:[1,0]
	v_pk_mul_f32 v[128:129], v[128:129], v[232:233] op_sel_hi:[1,0]
	v_pk_mul_f32 v[122:123], v[122:123], v[232:233] op_sel_hi:[1,0]
	v_pk_mul_f32 v[124:125], v[124:125], v[232:233] op_sel_hi:[1,0]
	v_max_f32_e32 v126, 0, v126
	v_max_f32_e32 v127, 0, v127
	v_max_f32_e32 v128, 0, v128
	v_max_f32_e32 v129, 0, v129
	v_max_f32_e32 v122, 0, v122
	v_max_f32_e32 v123, 0, v123
	v_max_f32_e32 v124, 0, v124
	v_max_f32_e32 v125, 0, v125
	v_pk_mul_f32 v[126:127], v[126:127], v[126:127]
	v_pk_mul_f32 v[128:129], v[128:129], v[128:129]
	v_pk_mul_f32 v[122:123], v[122:123], v[122:123]
	v_pk_mul_f32 v[124:125], v[124:125], v[124:125]
	v_cvt_pk_bf16_f32 v126, v126, v127
	v_cvt_pk_bf16_f32 v127, v128, v129
	v_cvt_pk_bf16_f32 v128, v122, v123
	v_cvt_pk_bf16_f32 v129, v124, v125
	buffer_store_dwordx4 v[126:129], v141, s[44:47], 0 offen sc1
	v_pk_mul_f32 v[118:119], v[118:119], v[232:233] op_sel_hi:[1,0]
	v_pk_mul_f32 v[120:121], v[120:121], v[232:233] op_sel_hi:[1,0]
	v_pk_mul_f32 v[114:115], v[114:115], v[232:233] op_sel_hi:[1,0]
	v_pk_mul_f32 v[116:117], v[116:117], v[232:233] op_sel_hi:[1,0]
	v_max_f32_e32 v118, 0, v118
	v_max_f32_e32 v119, 0, v119
	v_max_f32_e32 v120, 0, v120
	v_max_f32_e32 v121, 0, v121
	v_max_f32_e32 v114, 0, v114
	v_max_f32_e32 v115, 0, v115
	v_max_f32_e32 v116, 0, v116
	v_max_f32_e32 v117, 0, v117
	v_pk_mul_f32 v[118:119], v[118:119], v[118:119]
	v_pk_mul_f32 v[120:121], v[120:121], v[120:121]
	v_pk_mul_f32 v[114:115], v[114:115], v[114:115]
	v_pk_mul_f32 v[116:117], v[116:117], v[116:117]
	v_cvt_pk_bf16_f32 v118, v118, v119
	v_cvt_pk_bf16_f32 v119, v120, v121
	v_cvt_pk_bf16_f32 v120, v114, v115
	v_cvt_pk_bf16_f32 v121, v116, v117
	buffer_store_dwordx4 v[118:121], v141, s[44:47], 0 offen offset:256 sc1
	s_mov_b32 s100, 0x20000
	v_pk_mul_f32 v[110:111], v[110:111], v[234:235] op_sel_hi:[1,0]
	v_pk_mul_f32 v[112:113], v[112:113], v[234:235] op_sel_hi:[1,0]
	v_pk_mul_f32 v[106:107], v[106:107], v[234:235] op_sel_hi:[1,0]
	v_pk_mul_f32 v[108:109], v[108:109], v[234:235] op_sel_hi:[1,0]
	v_max_f32_e32 v110, 0, v110
	v_max_f32_e32 v111, 0, v111
	v_max_f32_e32 v112, 0, v112
	v_max_f32_e32 v113, 0, v113
	v_max_f32_e32 v106, 0, v106
	v_max_f32_e32 v107, 0, v107
	v_max_f32_e32 v108, 0, v108
	v_max_f32_e32 v109, 0, v109
	v_pk_mul_f32 v[110:111], v[110:111], v[110:111]
	v_pk_mul_f32 v[112:113], v[112:113], v[112:113]
	v_pk_mul_f32 v[106:107], v[106:107], v[106:107]
	v_pk_mul_f32 v[108:109], v[108:109], v[108:109]
	v_cvt_pk_bf16_f32 v110, v110, v111
	v_cvt_pk_bf16_f32 v111, v112, v113
	v_cvt_pk_bf16_f32 v112, v106, v107
	v_cvt_pk_bf16_f32 v113, v108, v109
	buffer_store_dwordx4 v[110:113], v141, s[44:47], s100 offen sc1
	v_pk_mul_f32 v[102:103], v[102:103], v[234:235] op_sel_hi:[1,0]
	v_pk_mul_f32 v[104:105], v[104:105], v[234:235] op_sel_hi:[1,0]
	v_pk_mul_f32 v[98:99], v[98:99], v[234:235] op_sel_hi:[1,0]
	v_pk_mul_f32 v[100:101], v[100:101], v[234:235] op_sel_hi:[1,0]
	v_max_f32_e32 v102, 0, v102
	v_max_f32_e32 v103, 0, v103
	v_max_f32_e32 v104, 0, v104
	v_max_f32_e32 v105, 0, v105
	v_max_f32_e32 v98, 0, v98
	v_max_f32_e32 v99, 0, v99
	v_max_f32_e32 v100, 0, v100
	v_max_f32_e32 v101, 0, v101
	v_pk_mul_f32 v[102:103], v[102:103], v[102:103]
	v_pk_mul_f32 v[104:105], v[104:105], v[104:105]
	v_pk_mul_f32 v[98:99], v[98:99], v[98:99]
	v_pk_mul_f32 v[100:101], v[100:101], v[100:101]
	v_cvt_pk_bf16_f32 v102, v102, v103
	v_cvt_pk_bf16_f32 v103, v104, v105
	v_cvt_pk_bf16_f32 v104, v98, v99
	v_cvt_pk_bf16_f32 v105, v100, v101
	buffer_store_dwordx4 v[102:105], v141, s[44:47], s100 offen offset:256 sc1
	s_mov_b32 s100, 0x40000
	v_pk_mul_f32 v[94:95], v[94:95], v[236:237] op_sel_hi:[1,0]
	v_pk_mul_f32 v[96:97], v[96:97], v[236:237] op_sel_hi:[1,0]
	v_pk_mul_f32 v[90:91], v[90:91], v[236:237] op_sel_hi:[1,0]
	v_pk_mul_f32 v[92:93], v[92:93], v[236:237] op_sel_hi:[1,0]
	v_max_f32_e32 v94, 0, v94
	v_max_f32_e32 v95, 0, v95
	v_max_f32_e32 v96, 0, v96
	v_max_f32_e32 v97, 0, v97
	v_max_f32_e32 v90, 0, v90
	v_max_f32_e32 v91, 0, v91
	v_max_f32_e32 v92, 0, v92
	v_max_f32_e32 v93, 0, v93
	v_pk_mul_f32 v[94:95], v[94:95], v[94:95]
	v_pk_mul_f32 v[96:97], v[96:97], v[96:97]
	v_pk_mul_f32 v[90:91], v[90:91], v[90:91]
	v_pk_mul_f32 v[92:93], v[92:93], v[92:93]
	v_cvt_pk_bf16_f32 v94, v94, v95
	v_cvt_pk_bf16_f32 v95, v96, v97
	v_cvt_pk_bf16_f32 v96, v90, v91
	v_cvt_pk_bf16_f32 v97, v92, v93
	buffer_store_dwordx4 v[94:97], v141, s[44:47], s100 offen sc1
	v_pk_mul_f32 v[86:87], v[86:87], v[236:237] op_sel_hi:[1,0]
	v_pk_mul_f32 v[88:89], v[88:89], v[236:237] op_sel_hi:[1,0]
	v_pk_mul_f32 v[82:83], v[82:83], v[236:237] op_sel_hi:[1,0]
	v_pk_mul_f32 v[84:85], v[84:85], v[236:237] op_sel_hi:[1,0]
	v_max_f32_e32 v86, 0, v86
	v_max_f32_e32 v87, 0, v87
	v_max_f32_e32 v88, 0, v88
	v_max_f32_e32 v89, 0, v89
	v_max_f32_e32 v82, 0, v82
	v_max_f32_e32 v83, 0, v83
	v_max_f32_e32 v84, 0, v84
	v_max_f32_e32 v85, 0, v85
	v_pk_mul_f32 v[86:87], v[86:87], v[86:87]
	v_pk_mul_f32 v[88:89], v[88:89], v[88:89]
	v_pk_mul_f32 v[82:83], v[82:83], v[82:83]
	v_pk_mul_f32 v[84:85], v[84:85], v[84:85]
	v_cvt_pk_bf16_f32 v86, v86, v87
	v_cvt_pk_bf16_f32 v87, v88, v89
	v_cvt_pk_bf16_f32 v88, v82, v83
	v_cvt_pk_bf16_f32 v89, v84, v85
	buffer_store_dwordx4 v[86:89], v141, s[44:47], s100 offen offset:256 sc1
	s_mov_b32 s100, 0x60000
	v_pk_mul_f32 v[78:79], v[78:79], v[238:239] op_sel_hi:[1,0]
	v_pk_mul_f32 v[80:81], v[80:81], v[238:239] op_sel_hi:[1,0]
	v_pk_mul_f32 v[74:75], v[74:75], v[238:239] op_sel_hi:[1,0]
	v_pk_mul_f32 v[76:77], v[76:77], v[238:239] op_sel_hi:[1,0]
	v_max_f32_e32 v78, 0, v78
	v_max_f32_e32 v79, 0, v79
	v_max_f32_e32 v80, 0, v80
	v_max_f32_e32 v81, 0, v81
	v_max_f32_e32 v74, 0, v74
	v_max_f32_e32 v75, 0, v75
	v_max_f32_e32 v76, 0, v76
	v_max_f32_e32 v77, 0, v77
	v_pk_mul_f32 v[78:79], v[78:79], v[78:79]
	v_pk_mul_f32 v[80:81], v[80:81], v[80:81]
	v_pk_mul_f32 v[74:75], v[74:75], v[74:75]
	v_pk_mul_f32 v[76:77], v[76:77], v[76:77]
	v_cvt_pk_bf16_f32 v78, v78, v79
	v_cvt_pk_bf16_f32 v79, v80, v81
	v_cvt_pk_bf16_f32 v80, v74, v75
	v_cvt_pk_bf16_f32 v81, v76, v77
	buffer_store_dwordx4 v[78:81], v141, s[44:47], s100 offen sc1
	v_pk_mul_f32 v[70:71], v[70:71], v[238:239] op_sel_hi:[1,0]
	v_pk_mul_f32 v[72:73], v[72:73], v[238:239] op_sel_hi:[1,0]
	v_pk_mul_f32 v[66:67], v[66:67], v[238:239] op_sel_hi:[1,0]
	v_pk_mul_f32 v[68:69], v[68:69], v[238:239] op_sel_hi:[1,0]
	v_max_f32_e32 v70, 0, v70
	v_max_f32_e32 v71, 0, v71
	v_max_f32_e32 v72, 0, v72
	v_max_f32_e32 v73, 0, v73
	v_max_f32_e32 v66, 0, v66
	v_max_f32_e32 v67, 0, v67
	v_max_f32_e32 v68, 0, v68
	v_max_f32_e32 v69, 0, v69
	v_pk_mul_f32 v[70:71], v[70:71], v[70:71]
	v_pk_mul_f32 v[72:73], v[72:73], v[72:73]
	v_pk_mul_f32 v[66:67], v[66:67], v[66:67]
	v_pk_mul_f32 v[68:69], v[68:69], v[68:69]
	v_cvt_pk_bf16_f32 v70, v70, v71
	v_cvt_pk_bf16_f32 v71, v72, v73
	v_cvt_pk_bf16_f32 v72, v66, v67
	v_cvt_pk_bf16_f32 v73, v68, v69
	buffer_store_dwordx4 v[70:73], v141, s[44:47], s100 offen offset:256 sc1
	s_mov_b32 s100, 0x100000
	v_pk_mul_f32 v[62:63], v[62:63], v[240:241] op_sel_hi:[1,0]
	v_pk_mul_f32 v[64:65], v[64:65], v[240:241] op_sel_hi:[1,0]
	v_pk_mul_f32 v[58:59], v[58:59], v[240:241] op_sel_hi:[1,0]
	v_pk_mul_f32 v[60:61], v[60:61], v[240:241] op_sel_hi:[1,0]
	v_max_f32_e32 v62, 0, v62
	v_max_f32_e32 v63, 0, v63
	v_max_f32_e32 v64, 0, v64
	v_max_f32_e32 v65, 0, v65
	v_max_f32_e32 v58, 0, v58
	v_max_f32_e32 v59, 0, v59
	v_max_f32_e32 v60, 0, v60
	v_max_f32_e32 v61, 0, v61
	v_pk_mul_f32 v[62:63], v[62:63], v[62:63]
	v_pk_mul_f32 v[64:65], v[64:65], v[64:65]
	v_pk_mul_f32 v[58:59], v[58:59], v[58:59]
	v_pk_mul_f32 v[60:61], v[60:61], v[60:61]
	v_cvt_pk_bf16_f32 v62, v62, v63
	v_cvt_pk_bf16_f32 v63, v64, v65
	v_cvt_pk_bf16_f32 v64, v58, v59
	v_cvt_pk_bf16_f32 v65, v60, v61
	buffer_store_dwordx4 v[62:65], v141, s[44:47], s100 offen sc1
	v_pk_mul_f32 v[54:55], v[54:55], v[240:241] op_sel_hi:[1,0]
	v_pk_mul_f32 v[56:57], v[56:57], v[240:241] op_sel_hi:[1,0]
	v_pk_mul_f32 v[50:51], v[50:51], v[240:241] op_sel_hi:[1,0]
	v_pk_mul_f32 v[52:53], v[52:53], v[240:241] op_sel_hi:[1,0]
	v_max_f32_e32 v54, 0, v54
	v_max_f32_e32 v55, 0, v55
	v_max_f32_e32 v56, 0, v56
	v_max_f32_e32 v57, 0, v57
	v_max_f32_e32 v50, 0, v50
	v_max_f32_e32 v51, 0, v51
	v_max_f32_e32 v52, 0, v52
	v_max_f32_e32 v53, 0, v53
	v_pk_mul_f32 v[54:55], v[54:55], v[54:55]
	v_pk_mul_f32 v[56:57], v[56:57], v[56:57]
	v_pk_mul_f32 v[50:51], v[50:51], v[50:51]
	v_pk_mul_f32 v[52:53], v[52:53], v[52:53]
	v_cvt_pk_bf16_f32 v54, v54, v55
	v_cvt_pk_bf16_f32 v55, v56, v57
	v_cvt_pk_bf16_f32 v56, v50, v51
	v_cvt_pk_bf16_f32 v57, v52, v53
	buffer_store_dwordx4 v[54:57], v141, s[44:47], s100 offen offset:256 sc1
	s_mov_b32 s100, 0x120000
	v_pk_mul_f32 v[46:47], v[46:47], v[242:243] op_sel_hi:[1,0]
	v_pk_mul_f32 v[48:49], v[48:49], v[242:243] op_sel_hi:[1,0]
	v_pk_mul_f32 v[42:43], v[42:43], v[242:243] op_sel_hi:[1,0]
	v_pk_mul_f32 v[44:45], v[44:45], v[242:243] op_sel_hi:[1,0]
	v_max_f32_e32 v46, 0, v46
	v_max_f32_e32 v47, 0, v47
	v_max_f32_e32 v48, 0, v48
	v_max_f32_e32 v49, 0, v49
	v_max_f32_e32 v42, 0, v42
	v_max_f32_e32 v43, 0, v43
	v_max_f32_e32 v44, 0, v44
	v_max_f32_e32 v45, 0, v45
	v_pk_mul_f32 v[46:47], v[46:47], v[46:47]
	v_pk_mul_f32 v[48:49], v[48:49], v[48:49]
	v_pk_mul_f32 v[42:43], v[42:43], v[42:43]
	v_pk_mul_f32 v[44:45], v[44:45], v[44:45]
	v_cvt_pk_bf16_f32 v46, v46, v47
	v_cvt_pk_bf16_f32 v47, v48, v49
	v_cvt_pk_bf16_f32 v48, v42, v43
	v_cvt_pk_bf16_f32 v49, v44, v45
	buffer_store_dwordx4 v[46:49], v141, s[44:47], s100 offen sc1
	v_pk_mul_f32 v[38:39], v[38:39], v[242:243] op_sel_hi:[1,0]
	v_pk_mul_f32 v[40:41], v[40:41], v[242:243] op_sel_hi:[1,0]
	v_pk_mul_f32 v[34:35], v[34:35], v[242:243] op_sel_hi:[1,0]
	v_pk_mul_f32 v[36:37], v[36:37], v[242:243] op_sel_hi:[1,0]
	v_max_f32_e32 v38, 0, v38
	v_max_f32_e32 v39, 0, v39
	v_max_f32_e32 v40, 0, v40
	v_max_f32_e32 v41, 0, v41
	v_max_f32_e32 v34, 0, v34
	v_max_f32_e32 v35, 0, v35
	v_max_f32_e32 v36, 0, v36
	v_max_f32_e32 v37, 0, v37
	v_pk_mul_f32 v[38:39], v[38:39], v[38:39]
	v_pk_mul_f32 v[40:41], v[40:41], v[40:41]
	v_pk_mul_f32 v[34:35], v[34:35], v[34:35]
	v_pk_mul_f32 v[36:37], v[36:37], v[36:37]
	v_cvt_pk_bf16_f32 v38, v38, v39
	v_cvt_pk_bf16_f32 v39, v40, v41
	v_cvt_pk_bf16_f32 v40, v34, v35
	v_cvt_pk_bf16_f32 v41, v36, v37
	buffer_store_dwordx4 v[38:41], v141, s[44:47], s100 offen offset:256 sc1
	s_mov_b32 s100, 0x140000
	v_pk_mul_f32 v[30:31], v[30:31], v[244:245] op_sel_hi:[1,0]
	v_pk_mul_f32 v[32:33], v[32:33], v[244:245] op_sel_hi:[1,0]
	v_pk_mul_f32 v[26:27], v[26:27], v[244:245] op_sel_hi:[1,0]
	v_pk_mul_f32 v[28:29], v[28:29], v[244:245] op_sel_hi:[1,0]
	v_max_f32_e32 v30, 0, v30
	v_max_f32_e32 v31, 0, v31
	v_max_f32_e32 v32, 0, v32
	v_max_f32_e32 v33, 0, v33
	v_max_f32_e32 v26, 0, v26
	v_max_f32_e32 v27, 0, v27
	v_max_f32_e32 v28, 0, v28
	v_max_f32_e32 v29, 0, v29
	v_pk_mul_f32 v[30:31], v[30:31], v[30:31]
	v_pk_mul_f32 v[32:33], v[32:33], v[32:33]
	v_pk_mul_f32 v[26:27], v[26:27], v[26:27]
	v_pk_mul_f32 v[28:29], v[28:29], v[28:29]
	v_cvt_pk_bf16_f32 v30, v30, v31
	v_cvt_pk_bf16_f32 v31, v32, v33
	v_cvt_pk_bf16_f32 v32, v26, v27
	v_cvt_pk_bf16_f32 v33, v28, v29
	buffer_store_dwordx4 v[30:33], v141, s[44:47], s100 offen sc1
	v_pk_mul_f32 v[22:23], v[22:23], v[244:245] op_sel_hi:[1,0]
	v_pk_mul_f32 v[24:25], v[24:25], v[244:245] op_sel_hi:[1,0]
	v_pk_mul_f32 v[18:19], v[18:19], v[244:245] op_sel_hi:[1,0]
	v_pk_mul_f32 v[20:21], v[20:21], v[244:245] op_sel_hi:[1,0]
	v_max_f32_e32 v22, 0, v22
	v_max_f32_e32 v23, 0, v23
	v_max_f32_e32 v24, 0, v24
	v_max_f32_e32 v25, 0, v25
	v_max_f32_e32 v18, 0, v18
	v_max_f32_e32 v19, 0, v19
	v_max_f32_e32 v20, 0, v20
	v_max_f32_e32 v21, 0, v21
	v_pk_mul_f32 v[22:23], v[22:23], v[22:23]
	v_pk_mul_f32 v[24:25], v[24:25], v[24:25]
	v_pk_mul_f32 v[18:19], v[18:19], v[18:19]
	v_pk_mul_f32 v[20:21], v[20:21], v[20:21]
	v_cvt_pk_bf16_f32 v22, v22, v23
	v_cvt_pk_bf16_f32 v23, v24, v25
	v_cvt_pk_bf16_f32 v24, v18, v19
	v_cvt_pk_bf16_f32 v25, v20, v21
	buffer_store_dwordx4 v[22:25], v141, s[44:47], s100 offen offset:256 sc1
	s_mov_b32 s100, 0x160000
	v_pk_mul_f32 v[14:15], v[14:15], v[246:247] op_sel_hi:[1,0]
	v_pk_mul_f32 v[16:17], v[16:17], v[246:247] op_sel_hi:[1,0]
	v_pk_mul_f32 v[10:11], v[10:11], v[246:247] op_sel_hi:[1,0]
	v_pk_mul_f32 v[12:13], v[12:13], v[246:247] op_sel_hi:[1,0]
	v_max_f32_e32 v14, 0, v14
	v_max_f32_e32 v15, 0, v15
	v_max_f32_e32 v16, 0, v16
	v_max_f32_e32 v17, 0, v17
	v_max_f32_e32 v10, 0, v10
	v_max_f32_e32 v11, 0, v11
	v_max_f32_e32 v12, 0, v12
	v_max_f32_e32 v13, 0, v13
	v_pk_mul_f32 v[14:15], v[14:15], v[14:15]
	v_pk_mul_f32 v[16:17], v[16:17], v[16:17]
	v_pk_mul_f32 v[10:11], v[10:11], v[10:11]
	v_pk_mul_f32 v[12:13], v[12:13], v[12:13]
	v_cvt_pk_bf16_f32 v14, v14, v15
	v_cvt_pk_bf16_f32 v15, v16, v17
	v_cvt_pk_bf16_f32 v16, v10, v11
	v_cvt_pk_bf16_f32 v17, v12, v13
	buffer_store_dwordx4 v[14:17], v141, s[44:47], s100 offen sc1
	v_pk_mul_f32 v[6:7], v[6:7], v[246:247] op_sel_hi:[1,0]
	v_pk_mul_f32 v[8:9], v[8:9], v[246:247] op_sel_hi:[1,0]
	v_pk_mul_f32 v[2:3], v[2:3], v[246:247] op_sel_hi:[1,0]
	v_pk_mul_f32 v[4:5], v[4:5], v[246:247] op_sel_hi:[1,0]
	v_max_f32_e32 v6, 0, v6
	v_max_f32_e32 v7, 0, v7
	v_max_f32_e32 v8, 0, v8
	v_max_f32_e32 v9, 0, v9
	v_max_f32_e32 v2, 0, v2
	v_max_f32_e32 v3, 0, v3
	v_max_f32_e32 v4, 0, v4
	v_max_f32_e32 v5, 0, v5
	v_pk_mul_f32 v[6:7], v[6:7], v[6:7]
	v_pk_mul_f32 v[8:9], v[8:9], v[8:9]
	v_pk_mul_f32 v[2:3], v[2:3], v[2:3]
	v_pk_mul_f32 v[4:5], v[4:5], v[4:5]
	v_cvt_pk_bf16_f32 v6, v6, v7
	v_cvt_pk_bf16_f32 v7, v8, v9
	v_cvt_pk_bf16_f32 v8, v2, v3
	v_cvt_pk_bf16_f32 v9, v4, v5
	buffer_store_dwordx4 v[6:9], v141, s[44:47], s100 offen offset:256 sc1
	s_andn2_b64 vcc, exec, s[0:1]
	s_mov_b64 s[0:1], -1
	s_cbranch_vccnz .LBB0_437
	s_andn2_b64 vcc, exec, s[4:5]
	s_cbranch_vccnz .LBB0_436
	s_barrier
	s_branch .LBB0_436

.LBB0_1022:
	v_readlane_b32 s0, v255, 17
	s_or_b32 s26, s0, 2
	s_cmp_le_i32 s84, s24
	s_cselect_b64 s[2:3], -1, 0
	s_and_b64 s[0:1], s[2:3], s[4:5]
	s_andn2_b64 vcc, exec, s[0:1]
	s_cbranch_vccnz .LBB0_1054
	ds_read_b64 v[2:3], v231
	v_lshrrev_b32_e32 v227, 8, v0
	v_and_b32_e32 v247, 15, v0
	v_lshl_or_b32 v227, v227, 6, v247
	v_lshlrev_b32_e32 v227, 7, v227
	v_mov_b32_e32 v229, 0x3a800000
	s_and_b32 s100, s81, 7
	s_lshl_b32 s100, s100, 3
	s_bfe_u32 s101, s81, 0x30003
	s_add_i32 s100, s100, s101
	s_lshl_b32 s100, s100, 15
	s_waitcnt lgkmcnt(0)
	v_readfirstlane_b32 s98, v2
	v_readfirstlane_b32 s99, v3
	s_nop 3
	s_add_u32 s98, s98, s100
	s_addc_u32 s99, s99, 0
	s_add_u32 s98, s98, 0x10900000
	s_addc_u32 s99, s99, 0
	s_mov_b32 s100, s98
	s_mov_b32 s101, s99
	s_nop 0
	global_load_dwordx4 v[2:5], v227, s[100:101]
	global_load_dwordx4 v[6:9], v227, s[100:101] offset:16
	global_load_dwordx4 v[10:13], v227, s[100:101] offset:32
	global_load_dwordx4 v[14:17], v227, s[100:101] offset:48
	s_mov_b32 s100, s98
	s_mov_b32 s101, s99
	s_nop 0
	global_load_dwordx4 v[18:21], v227, s[100:101] offset:2048
	global_load_dwordx4 v[22:25], v227, s[100:101] offset:2064
	global_load_dwordx4 v[26:29], v227, s[100:101] offset:2080
	global_load_dwordx4 v[30:33], v227, s[100:101] offset:2096
	s_add_u32 s100, s98, 0x1000
	s_addc_u32 s101, s99, 0
	s_nop 0
	global_load_dwordx4 v[34:37], v227, s[100:101]
	global_load_dwordx4 v[38:41], v227, s[100:101] offset:16
	global_load_dwordx4 v[42:45], v227, s[100:101] offset:32
	global_load_dwordx4 v[46:49], v227, s[100:101] offset:48
	s_add_u32 s100, s98, 0x1000
	s_addc_u32 s101, s99, 0
	s_nop 0
	global_load_dwordx4 v[50:53], v227, s[100:101] offset:2048
	global_load_dwordx4 v[54:57], v227, s[100:101] offset:2064
	global_load_dwordx4 v[58:61], v227, s[100:101] offset:2080
	global_load_dwordx4 v[62:65], v227, s[100:101] offset:2096
	s_add_u32 s100, s98, 0x4000
	s_addc_u32 s101, s99, 0
	s_nop 0
	global_load_dwordx4 v[66:69], v227, s[100:101]
	global_load_dwordx4 v[70:73], v227, s[100:101] offset:16
	global_load_dwordx4 v[74:77], v227, s[100:101] offset:32
	global_load_dwordx4 v[78:81], v227, s[100:101] offset:48
	s_add_u32 s100, s98, 0x4000
	s_addc_u32 s101, s99, 0
	s_nop 0
	global_load_dwordx4 v[82:85], v227, s[100:101] offset:2048
	global_load_dwordx4 v[86:89], v227, s[100:101] offset:2064
	global_load_dwordx4 v[90:93], v227, s[100:101] offset:2080
	global_load_dwordx4 v[94:97], v227, s[100:101] offset:2096
	s_add_u32 s100, s98, 0x5000
	s_addc_u32 s101, s99, 0
	s_nop 0
	global_load_dwordx4 v[98:101], v227, s[100:101]
	global_load_dwordx4 v[102:105], v227, s[100:101] offset:16
	global_load_dwordx4 v[106:109], v227, s[100:101] offset:32
	global_load_dwordx4 v[110:113], v227, s[100:101] offset:48
	s_add_u32 s100, s98, 0x5000
	s_addc_u32 s101, s99, 0
	s_nop 0
	global_load_dwordx4 v[114:117], v227, s[100:101] offset:2048
	global_load_dwordx4 v[118:121], v227, s[100:101] offset:2064
	global_load_dwordx4 v[122:125], v227, s[100:101] offset:2080
	global_load_dwordx4 v[126:129], v227, s[100:101] offset:2096
	s_waitcnt vmcnt(28)
	v_add_f32_e32 v247, v2, v3
	v_add_f32_e32 v249, v4, v5
	v_add_f32_e32 v251, v247, v249
	v_add_f32_e32 v247, v6, v7
	v_add_f32_e32 v249, v8, v9
	v_add_f32_e32 v247, v247, v249
	v_add_f32_e32 v251, v251, v247
	v_add_f32_e32 v247, v10, v11
	v_add_f32_e32 v249, v12, v13
	v_add_f32_e32 v247, v247, v249
	v_add_f32_e32 v251, v251, v247
	v_add_f32_e32 v247, v14, v15
	v_add_f32_e32 v249, v16, v17
	v_add_f32_e32 v247, v247, v249
	v_add_f32_e32 v251, v251, v247
	v_fmaak_f32 v251, v229, v251, 0x358637bd
	v_rsq_f32_e32 v226, v251
	s_waitcnt vmcnt(24)
	v_add_f32_e32 v247, v18, v19
	v_add_f32_e32 v249, v20, v21
	v_add_f32_e32 v251, v247, v249
	v_add_f32_e32 v247, v22, v23
	v_add_f32_e32 v249, v24, v25
	v_add_f32_e32 v247, v247, v249
	v_add_f32_e32 v251, v251, v247
	v_add_f32_e32 v247, v26, v27
	v_add_f32_e32 v249, v28, v29
	v_add_f32_e32 v247, v247, v249
	v_add_f32_e32 v251, v251, v247
	v_add_f32_e32 v247, v30, v31
	v_add_f32_e32 v249, v32, v33
	v_add_f32_e32 v247, v247, v249
	v_add_f32_e32 v251, v251, v247
	v_fmaak_f32 v251, v229, v251, 0x358637bd
	v_rsq_f32_e32 v228, v251
	s_waitcnt vmcnt(20)
	v_add_f32_e32 v247, v34, v35
	v_add_f32_e32 v249, v36, v37
	v_add_f32_e32 v251, v247, v249
	v_add_f32_e32 v247, v38, v39
	v_add_f32_e32 v249, v40, v41
	v_add_f32_e32 v247, v247, v249
	v_add_f32_e32 v251, v251, v247
	v_add_f32_e32 v247, v42, v43
	v_add_f32_e32 v249, v44, v45
	v_add_f32_e32 v247, v247, v249
	v_add_f32_e32 v251, v251, v247
	v_add_f32_e32 v247, v46, v47
	v_add_f32_e32 v249, v48, v49
	v_add_f32_e32 v247, v247, v249
	v_add_f32_e32 v251, v251, v247
	v_fmaak_f32 v251, v229, v251, 0x358637bd
	v_rsq_f32_e32 v230, v251
	s_waitcnt vmcnt(16)
	v_add_f32_e32 v247, v50, v51
	v_add_f32_e32 v249, v52, v53
	v_add_f32_e32 v251, v247, v249
	v_add_f32_e32 v247, v54, v55
	v_add_f32_e32 v249, v56, v57
	v_add_f32_e32 v247, v247, v249
	v_add_f32_e32 v251, v251, v247
	v_add_f32_e32 v247, v58, v59
	v_add_f32_e32 v249, v60, v61
	v_add_f32_e32 v247, v247, v249
	v_add_f32_e32 v251, v251, v247
	v_add_f32_e32 v247, v62, v63
	v_add_f32_e32 v249, v64, v65
	v_add_f32_e32 v247, v247, v249
	v_add_f32_e32 v251, v251, v247
	v_fmaak_f32 v251, v229, v251, 0x358637bd
	v_rsq_f32_e32 v246, v251
	s_waitcnt vmcnt(12)
	v_add_f32_e32 v247, v66, v67
	v_add_f32_e32 v249, v68, v69
	v_add_f32_e32 v251, v247, v249
	v_add_f32_e32 v247, v70, v71
	v_add_f32_e32 v249, v72, v73
	v_add_f32_e32 v247, v247, v249
	v_add_f32_e32 v251, v251, v247
	v_add_f32_e32 v247, v74, v75
	v_add_f32_e32 v249, v76, v77
	v_add_f32_e32 v247, v247, v249
	v_add_f32_e32 v251, v251, v247
	v_add_f32_e32 v247, v78, v79
	v_add_f32_e32 v249, v80, v81
	v_add_f32_e32 v247, v247, v249
	v_add_f32_e32 v251, v251, v247
	v_fmaak_f32 v251, v229, v251, 0x358637bd
	v_rsq_f32_e32 v248, v251
	s_waitcnt vmcnt(8)
	v_add_f32_e32 v247, v82, v83
	v_add_f32_e32 v249, v84, v85
	v_add_f32_e32 v251, v247, v249
	v_add_f32_e32 v247, v86, v87
	v_add_f32_e32 v249, v88, v89
	v_add_f32_e32 v247, v247, v249
	v_add_f32_e32 v251, v251, v247
	v_add_f32_e32 v247, v90, v91
	v_add_f32_e32 v249, v92, v93
	v_add_f32_e32 v247, v247, v249
	v_add_f32_e32 v251, v251, v247
	v_add_f32_e32 v247, v94, v95
	v_add_f32_e32 v249, v96, v97
	v_add_f32_e32 v247, v247, v249
	v_add_f32_e32 v251, v251, v247
	v_fmaak_f32 v251, v229, v251, 0x358637bd
	v_rsq_f32_e32 v250, v251
	s_waitcnt vmcnt(4)
	v_add_f32_e32 v247, v98, v99
	v_add_f32_e32 v249, v100, v101
	v_add_f32_e32 v251, v247, v249
	v_add_f32_e32 v247, v102, v103
	v_add_f32_e32 v249, v104, v105
	v_add_f32_e32 v247, v247, v249
	v_add_f32_e32 v251, v251, v247
	v_add_f32_e32 v247, v106, v107
	v_add_f32_e32 v249, v108, v109
	v_add_f32_e32 v247, v247, v249
	v_add_f32_e32 v251, v251, v247
	v_add_f32_e32 v247, v110, v111
	v_add_f32_e32 v249, v112, v113
	v_add_f32_e32 v247, v247, v249
	v_add_f32_e32 v251, v251, v247
	v_fmaak_f32 v251, v229, v251, 0x358637bd
	v_rsq_f32_e32 v252, v251
	s_waitcnt vmcnt(0)
	v_add_f32_e32 v247, v114, v115
	v_add_f32_e32 v249, v116, v117
	v_add_f32_e32 v251, v247, v249
	v_add_f32_e32 v247, v118, v119
	v_add_f32_e32 v249, v120, v121
	v_add_f32_e32 v247, v247, v249
	v_add_f32_e32 v251, v251, v247
	v_add_f32_e32 v247, v122, v123
	v_add_f32_e32 v249, v124, v125
	v_add_f32_e32 v247, v247, v249
	v_add_f32_e32 v251, v251, v247
	v_add_f32_e32 v247, v126, v127
	v_add_f32_e32 v249, v128, v129
	v_add_f32_e32 v247, v247, v249
	v_add_f32_e32 v251, v251, v247
	v_fmaak_f32 v251, v229, v251, 0x358637bd
	v_rsq_f32_e32 v254, v251
	s_lshl_b32 s27, s26, 22
	s_mov_b32 s28, s81
	s_waitcnt lgkmcnt(0)
	ds_read_b64 v[2:3], v231
	s_waitcnt lgkmcnt(0)
	s_waitcnt vmcnt(0)
	v_mov_b32 v10, v0
	s_cmpk_gt_i32 s28, 0x3ff
	v_readfirstlane_b32 s89, v3
	v_readfirstlane_b32 s88, v2
	v_readfirstlane_b32 s8, v10
	s_cbranch_scc1 .LBB0_1047
	s_ashr_i32 s29, s28, 31
	s_lshr_b32 s0, s29, 29
	s_add_i32 s6, s28, s0
	s_and_b32 s0, s6, -8
	s_sub_i32 s5, s28, s0
	s_cmp_gt_i32 s5, -1
	s_mov_b64 s[0:1], -1
	s_cbranch_scc0 .LBB0_1026
	s_lshl_b32 s4, s5, 7
	s_mov_b64 s[0:1], 0

.LBB0_1043:
	v_lshl_add_u32 v140, s18, 8, v144
	v_lshl_add_u32 v141, s45, 9, v146
	v_lshl_add_u32 v141, v140, 13, v141
	v_pk_mul_f32 v[126:127], v[126:127], v[226:227] op_sel_hi:[1,0]
	v_pk_mul_f32 v[128:129], v[128:129], v[226:227] op_sel_hi:[1,0]
	v_pk_mul_f32 v[122:123], v[122:123], v[226:227] op_sel_hi:[1,0]
	v_pk_mul_f32 v[124:125], v[124:125], v[226:227] op_sel_hi:[1,0]
	v_max_f32_e32 v126, 0, v126
	v_max_f32_e32 v127, 0, v127
	v_max_f32_e32 v128, 0, v128
	v_max_f32_e32 v129, 0, v129
	v_max_f32_e32 v122, 0, v122
	v_max_f32_e32 v123, 0, v123
	v_max_f32_e32 v124, 0, v124
	v_max_f32_e32 v125, 0, v125
	v_pk_mul_f32 v[126:127], v[126:127], v[126:127]
	v_pk_mul_f32 v[128:129], v[128:129], v[128:129]
	v_pk_mul_f32 v[122:123], v[122:123], v[122:123]
	v_pk_mul_f32 v[124:125], v[124:125], v[124:125]
	v_cvt_pk_bf16_f32 v126, v126, v127
	v_cvt_pk_bf16_f32 v127, v128, v129
	v_cvt_pk_bf16_f32 v128, v122, v123
	v_cvt_pk_bf16_f32 v129, v124, v125
	buffer_store_dwordx4 v[126:129], v141, s[88:91], 0 offen sc1
	v_pk_mul_f32 v[118:119], v[118:119], v[226:227] op_sel_hi:[1,0]
	v_pk_mul_f32 v[120:121], v[120:121], v[226:227] op_sel_hi:[1,0]
	v_pk_mul_f32 v[114:115], v[114:115], v[226:227] op_sel_hi:[1,0]
	v_pk_mul_f32 v[116:117], v[116:117], v[226:227] op_sel_hi:[1,0]
	v_max_f32_e32 v118, 0, v118
	v_max_f32_e32 v119, 0, v119
	v_max_f32_e32 v120, 0, v120
	v_max_f32_e32 v121, 0, v121
	v_max_f32_e32 v114, 0, v114
	v_max_f32_e32 v115, 0, v115
	v_max_f32_e32 v116, 0, v116
	v_max_f32_e32 v117, 0, v117
	v_pk_mul_f32 v[118:119], v[118:119], v[118:119]
	v_pk_mul_f32 v[120:121], v[120:121], v[120:121]
	v_pk_mul_f32 v[114:115], v[114:115], v[114:115]
	v_pk_mul_f32 v[116:117], v[116:117], v[116:117]
	v_cvt_pk_bf16_f32 v118, v118, v119
	v_cvt_pk_bf16_f32 v119, v120, v121
	v_cvt_pk_bf16_f32 v120, v114, v115
	v_cvt_pk_bf16_f32 v121, v116, v117
	buffer_store_dwordx4 v[118:121], v141, s[88:91], 0 offen offset:256 sc1
	s_mov_b32 s100, 0x20000
	v_pk_mul_f32 v[110:111], v[110:111], v[228:229] op_sel_hi:[1,0]
	v_pk_mul_f32 v[112:113], v[112:113], v[228:229] op_sel_hi:[1,0]
	v_pk_mul_f32 v[106:107], v[106:107], v[228:229] op_sel_hi:[1,0]
	v_pk_mul_f32 v[108:109], v[108:109], v[228:229] op_sel_hi:[1,0]
	v_max_f32_e32 v110, 0, v110
	v_max_f32_e32 v111, 0, v111
	v_max_f32_e32 v112, 0, v112
	v_max_f32_e32 v113, 0, v113
	v_max_f32_e32 v106, 0, v106
	v_max_f32_e32 v107, 0, v107
	v_max_f32_e32 v108, 0, v108
	v_max_f32_e32 v109, 0, v109
	v_pk_mul_f32 v[110:111], v[110:111], v[110:111]
	v_pk_mul_f32 v[112:113], v[112:113], v[112:113]
	v_pk_mul_f32 v[106:107], v[106:107], v[106:107]
	v_pk_mul_f32 v[108:109], v[108:109], v[108:109]
	v_cvt_pk_bf16_f32 v110, v110, v111
	v_cvt_pk_bf16_f32 v111, v112, v113
	v_cvt_pk_bf16_f32 v112, v106, v107
	v_cvt_pk_bf16_f32 v113, v108, v109
	buffer_store_dwordx4 v[110:113], v141, s[88:91], s100 offen sc1
	v_pk_mul_f32 v[102:103], v[102:103], v[228:229] op_sel_hi:[1,0]
	v_pk_mul_f32 v[104:105], v[104:105], v[228:229] op_sel_hi:[1,0]
	v_pk_mul_f32 v[98:99], v[98:99], v[228:229] op_sel_hi:[1,0]
	v_pk_mul_f32 v[100:101], v[100:101], v[228:229] op_sel_hi:[1,0]
	v_max_f32_e32 v102, 0, v102
	v_max_f32_e32 v103, 0, v103
	v_max_f32_e32 v104, 0, v104
	v_max_f32_e32 v105, 0, v105
	v_max_f32_e32 v98, 0, v98
	v_max_f32_e32 v99, 0, v99
	v_max_f32_e32 v100, 0, v100
	v_max_f32_e32 v101, 0, v101
	v_pk_mul_f32 v[102:103], v[102:103], v[102:103]
	v_pk_mul_f32 v[104:105], v[104:105], v[104:105]
	v_pk_mul_f32 v[98:99], v[98:99], v[98:99]
	v_pk_mul_f32 v[100:101], v[100:101], v[100:101]
	v_cvt_pk_bf16_f32 v102, v102, v103
	v_cvt_pk_bf16_f32 v103, v104, v105
	v_cvt_pk_bf16_f32 v104, v98, v99
	v_cvt_pk_bf16_f32 v105, v100, v101
	buffer_store_dwordx4 v[102:105], v141, s[88:91], s100 offen offset:256 sc1
	s_mov_b32 s100, 0x40000
	v_pk_mul_f32 v[94:95], v[94:95], v[230:231] op_sel_hi:[1,0]
	v_pk_mul_f32 v[96:97], v[96:97], v[230:231] op_sel_hi:[1,0]
	v_pk_mul_f32 v[90:91], v[90:91], v[230:231] op_sel_hi:[1,0]
	v_pk_mul_f32 v[92:93], v[92:93], v[230:231] op_sel_hi:[1,0]
	v_max_f32_e32 v94, 0, v94
	v_max_f32_e32 v95, 0, v95
	v_max_f32_e32 v96, 0, v96
	v_max_f32_e32 v97, 0, v97
	v_max_f32_e32 v90, 0, v90
	v_max_f32_e32 v91, 0, v91
	v_max_f32_e32 v92, 0, v92
	v_max_f32_e32 v93, 0, v93
	v_pk_mul_f32 v[94:95], v[94:95], v[94:95]
	v_pk_mul_f32 v[96:97], v[96:97], v[96:97]
	v_pk_mul_f32 v[90:91], v[90:91], v[90:91]
	v_pk_mul_f32 v[92:93], v[92:93], v[92:93]
	v_cvt_pk_bf16_f32 v94, v94, v95
	v_cvt_pk_bf16_f32 v95, v96, v97
	v_cvt_pk_bf16_f32 v96, v90, v91
	v_cvt_pk_bf16_f32 v97, v92, v93
	buffer_store_dwordx4 v[94:97], v141, s[88:91], s100 offen sc1
	v_pk_mul_f32 v[86:87], v[86:87], v[230:231] op_sel_hi:[1,0]
	v_pk_mul_f32 v[88:89], v[88:89], v[230:231] op_sel_hi:[1,0]
	v_pk_mul_f32 v[82:83], v[82:83], v[230:231] op_sel_hi:[1,0]
	v_pk_mul_f32 v[84:85], v[84:85], v[230:231] op_sel_hi:[1,0]
	v_max_f32_e32 v86, 0, v86
	v_max_f32_e32 v87, 0, v87
	v_max_f32_e32 v88, 0, v88
	v_max_f32_e32 v89, 0, v89
	v_max_f32_e32 v82, 0, v82
	v_max_f32_e32 v83, 0, v83
	v_max_f32_e32 v84, 0, v84
	v_max_f32_e32 v85, 0, v85
	v_pk_mul_f32 v[86:87], v[86:87], v[86:87]
	v_pk_mul_f32 v[88:89], v[88:89], v[88:89]
	v_pk_mul_f32 v[82:83], v[82:83], v[82:83]
	v_pk_mul_f32 v[84:85], v[84:85], v[84:85]
	v_cvt_pk_bf16_f32 v86, v86, v87
	v_cvt_pk_bf16_f32 v87, v88, v89
	v_cvt_pk_bf16_f32 v88, v82, v83
	v_cvt_pk_bf16_f32 v89, v84, v85
	buffer_store_dwordx4 v[86:89], v141, s[88:91], s100 offen offset:256 sc1
	s_mov_b32 s100, 0x60000
	v_pk_mul_f32 v[78:79], v[78:79], v[246:247] op_sel_hi:[1,0]
	v_pk_mul_f32 v[80:81], v[80:81], v[246:247] op_sel_hi:[1,0]
	v_pk_mul_f32 v[74:75], v[74:75], v[246:247] op_sel_hi:[1,0]
	v_pk_mul_f32 v[76:77], v[76:77], v[246:247] op_sel_hi:[1,0]
	v_max_f32_e32 v78, 0, v78
	v_max_f32_e32 v79, 0, v79
	v_max_f32_e32 v80, 0, v80
	v_max_f32_e32 v81, 0, v81
	v_max_f32_e32 v74, 0, v74
	v_max_f32_e32 v75, 0, v75
	v_max_f32_e32 v76, 0, v76
	v_max_f32_e32 v77, 0, v77
	v_pk_mul_f32 v[78:79], v[78:79], v[78:79]
	v_pk_mul_f32 v[80:81], v[80:81], v[80:81]
	v_pk_mul_f32 v[74:75], v[74:75], v[74:75]
	v_pk_mul_f32 v[76:77], v[76:77], v[76:77]
	v_cvt_pk_bf16_f32 v78, v78, v79
	v_cvt_pk_bf16_f32 v79, v80, v81
	v_cvt_pk_bf16_f32 v80, v74, v75
	v_cvt_pk_bf16_f32 v81, v76, v77
	buffer_store_dwordx4 v[78:81], v141, s[88:91], s100 offen sc1
	v_pk_mul_f32 v[70:71], v[70:71], v[246:247] op_sel_hi:[1,0]
	v_pk_mul_f32 v[72:73], v[72:73], v[246:247] op_sel_hi:[1,0]
	v_pk_mul_f32 v[66:67], v[66:67], v[246:247] op_sel_hi:[1,0]
	v_pk_mul_f32 v[68:69], v[68:69], v[246:247] op_sel_hi:[1,0]
	v_max_f32_e32 v70, 0, v70
	v_max_f32_e32 v71, 0, v71
	v_max_f32_e32 v72, 0, v72
	v_max_f32_e32 v73, 0, v73
	v_max_f32_e32 v66, 0, v66
	v_max_f32_e32 v67, 0, v67
	v_max_f32_e32 v68, 0, v68
	v_max_f32_e32 v69, 0, v69
	v_pk_mul_f32 v[70:71], v[70:71], v[70:71]
	v_pk_mul_f32 v[72:73], v[72:73], v[72:73]
	v_pk_mul_f32 v[66:67], v[66:67], v[66:67]
	v_pk_mul_f32 v[68:69], v[68:69], v[68:69]
	v_cvt_pk_bf16_f32 v70, v70, v71
	v_cvt_pk_bf16_f32 v71, v72, v73
	v_cvt_pk_bf16_f32 v72, v66, v67
	v_cvt_pk_bf16_f32 v73, v68, v69
	buffer_store_dwordx4 v[70:73], v141, s[88:91], s100 offen offset:256 sc1
	s_mov_b32 s100, 0x100000
	v_pk_mul_f32 v[62:63], v[62:63], v[248:249] op_sel_hi:[1,0]
	v_pk_mul_f32 v[64:65], v[64:65], v[248:249] op_sel_hi:[1,0]
	v_pk_mul_f32 v[58:59], v[58:59], v[248:249] op_sel_hi:[1,0]
	v_pk_mul_f32 v[60:61], v[60:61], v[248:249] op_sel_hi:[1,0]
	v_max_f32_e32 v62, 0, v62
	v_max_f32_e32 v63, 0, v63
	v_max_f32_e32 v64, 0, v64
	v_max_f32_e32 v65, 0, v65
	v_max_f32_e32 v58, 0, v58
	v_max_f32_e32 v59, 0, v59
	v_max_f32_e32 v60, 0, v60
	v_max_f32_e32 v61, 0, v61
	v_pk_mul_f32 v[62:63], v[62:63], v[62:63]
	v_pk_mul_f32 v[64:65], v[64:65], v[64:65]
	v_pk_mul_f32 v[58:59], v[58:59], v[58:59]
	v_pk_mul_f32 v[60:61], v[60:61], v[60:61]
	v_cvt_pk_bf16_f32 v62, v62, v63
	v_cvt_pk_bf16_f32 v63, v64, v65
	v_cvt_pk_bf16_f32 v64, v58, v59
	v_cvt_pk_bf16_f32 v65, v60, v61
	buffer_store_dwordx4 v[62:65], v141, s[88:91], s100 offen sc1
	v_pk_mul_f32 v[54:55], v[54:55], v[248:249] op_sel_hi:[1,0]
	v_pk_mul_f32 v[56:57], v[56:57], v[248:249] op_sel_hi:[1,0]
	v_pk_mul_f32 v[50:51], v[50:51], v[248:249] op_sel_hi:[1,0]
	v_pk_mul_f32 v[52:53], v[52:53], v[248:249] op_sel_hi:[1,0]
	v_max_f32_e32 v54, 0, v54
	v_max_f32_e32 v55, 0, v55
	v_max_f32_e32 v56, 0, v56
	v_max_f32_e32 v57, 0, v57
	v_max_f32_e32 v50, 0, v50
	v_max_f32_e32 v51, 0, v51
	v_max_f32_e32 v52, 0, v52
	v_max_f32_e32 v53, 0, v53
	v_pk_mul_f32 v[54:55], v[54:55], v[54:55]
	v_pk_mul_f32 v[56:57], v[56:57], v[56:57]
	v_pk_mul_f32 v[50:51], v[50:51], v[50:51]
	v_pk_mul_f32 v[52:53], v[52:53], v[52:53]
	v_cvt_pk_bf16_f32 v54, v54, v55
	v_cvt_pk_bf16_f32 v55, v56, v57
	v_cvt_pk_bf16_f32 v56, v50, v51
	v_cvt_pk_bf16_f32 v57, v52, v53
	buffer_store_dwordx4 v[54:57], v141, s[88:91], s100 offen offset:256 sc1
	s_mov_b32 s100, 0x120000
	v_pk_mul_f32 v[46:47], v[46:47], v[250:251] op_sel_hi:[1,0]
	v_pk_mul_f32 v[48:49], v[48:49], v[250:251] op_sel_hi:[1,0]
	v_pk_mul_f32 v[42:43], v[42:43], v[250:251] op_sel_hi:[1,0]
	v_pk_mul_f32 v[44:45], v[44:45], v[250:251] op_sel_hi:[1,0]
	v_max_f32_e32 v46, 0, v46
	v_max_f32_e32 v47, 0, v47
	v_max_f32_e32 v48, 0, v48
	v_max_f32_e32 v49, 0, v49
	v_max_f32_e32 v42, 0, v42
	v_max_f32_e32 v43, 0, v43
	v_max_f32_e32 v44, 0, v44
	v_max_f32_e32 v45, 0, v45
	v_pk_mul_f32 v[46:47], v[46:47], v[46:47]
	v_pk_mul_f32 v[48:49], v[48:49], v[48:49]
	v_pk_mul_f32 v[42:43], v[42:43], v[42:43]
	v_pk_mul_f32 v[44:45], v[44:45], v[44:45]
	v_cvt_pk_bf16_f32 v46, v46, v47
	v_cvt_pk_bf16_f32 v47, v48, v49
	v_cvt_pk_bf16_f32 v48, v42, v43
	v_cvt_pk_bf16_f32 v49, v44, v45
	buffer_store_dwordx4 v[46:49], v141, s[88:91], s100 offen sc1
	v_pk_mul_f32 v[38:39], v[38:39], v[250:251] op_sel_hi:[1,0]
	v_pk_mul_f32 v[40:41], v[40:41], v[250:251] op_sel_hi:[1,0]
	v_pk_mul_f32 v[34:35], v[34:35], v[250:251] op_sel_hi:[1,0]
	v_pk_mul_f32 v[36:37], v[36:37], v[250:251] op_sel_hi:[1,0]
	v_max_f32_e32 v38, 0, v38
	v_max_f32_e32 v39, 0, v39
	v_max_f32_e32 v40, 0, v40
	v_max_f32_e32 v41, 0, v41
	v_max_f32_e32 v34, 0, v34
	v_max_f32_e32 v35, 0, v35
	v_max_f32_e32 v36, 0, v36
	v_max_f32_e32 v37, 0, v37
	v_pk_mul_f32 v[38:39], v[38:39], v[38:39]
	v_pk_mul_f32 v[40:41], v[40:41], v[40:41]
	v_pk_mul_f32 v[34:35], v[34:35], v[34:35]
	v_pk_mul_f32 v[36:37], v[36:37], v[36:37]
	v_cvt_pk_bf16_f32 v38, v38, v39
	v_cvt_pk_bf16_f32 v39, v40, v41
	v_cvt_pk_bf16_f32 v40, v34, v35
	v_cvt_pk_bf16_f32 v41, v36, v37
	buffer_store_dwordx4 v[38:41], v141, s[88:91], s100 offen offset:256 sc1
	s_mov_b32 s100, 0x140000
	v_pk_mul_f32 v[30:31], v[30:31], v[252:253] op_sel_hi:[1,0]
	v_pk_mul_f32 v[32:33], v[32:33], v[252:253] op_sel_hi:[1,0]
	v_pk_mul_f32 v[26:27], v[26:27], v[252:253] op_sel_hi:[1,0]
	v_pk_mul_f32 v[28:29], v[28:29], v[252:253] op_sel_hi:[1,0]
	v_max_f32_e32 v30, 0, v30
	v_max_f32_e32 v31, 0, v31
	v_max_f32_e32 v32, 0, v32
	v_max_f32_e32 v33, 0, v33
	v_max_f32_e32 v26, 0, v26
	v_max_f32_e32 v27, 0, v27
	v_max_f32_e32 v28, 0, v28
	v_max_f32_e32 v29, 0, v29
	v_pk_mul_f32 v[30:31], v[30:31], v[30:31]
	v_pk_mul_f32 v[32:33], v[32:33], v[32:33]
	v_pk_mul_f32 v[26:27], v[26:27], v[26:27]
	v_pk_mul_f32 v[28:29], v[28:29], v[28:29]
	v_cvt_pk_bf16_f32 v30, v30, v31
	v_cvt_pk_bf16_f32 v31, v32, v33
	v_cvt_pk_bf16_f32 v32, v26, v27
	v_cvt_pk_bf16_f32 v33, v28, v29
	buffer_store_dwordx4 v[30:33], v141, s[88:91], s100 offen sc1
	v_pk_mul_f32 v[22:23], v[22:23], v[252:253] op_sel_hi:[1,0]
	v_pk_mul_f32 v[24:25], v[24:25], v[252:253] op_sel_hi:[1,0]
	v_pk_mul_f32 v[18:19], v[18:19], v[252:253] op_sel_hi:[1,0]
	v_pk_mul_f32 v[20:21], v[20:21], v[252:253] op_sel_hi:[1,0]
	v_max_f32_e32 v22, 0, v22
	v_max_f32_e32 v23, 0, v23
	v_max_f32_e32 v24, 0, v24
	v_max_f32_e32 v25, 0, v25
	v_max_f32_e32 v18, 0, v18
	v_max_f32_e32 v19, 0, v19
	v_max_f32_e32 v20, 0, v20
	v_max_f32_e32 v21, 0, v21
	v_pk_mul_f32 v[22:23], v[22:23], v[22:23]
	v_pk_mul_f32 v[24:25], v[24:25], v[24:25]
	v_pk_mul_f32 v[18:19], v[18:19], v[18:19]
	v_pk_mul_f32 v[20:21], v[20:21], v[20:21]
	v_cvt_pk_bf16_f32 v22, v22, v23
	v_cvt_pk_bf16_f32 v23, v24, v25
	v_cvt_pk_bf16_f32 v24, v18, v19
	v_cvt_pk_bf16_f32 v25, v20, v21
	buffer_store_dwordx4 v[22:25], v141, s[88:91], s100 offen offset:256 sc1
	s_mov_b32 s100, 0x160000
	v_pk_mul_f32 v[14:15], v[14:15], v[254:255] op_sel_hi:[1,0]
	v_pk_mul_f32 v[16:17], v[16:17], v[254:255] op_sel_hi:[1,0]
	v_pk_mul_f32 v[10:11], v[10:11], v[254:255] op_sel_hi:[1,0]
	v_pk_mul_f32 v[12:13], v[12:13], v[254:255] op_sel_hi:[1,0]
	v_max_f32_e32 v14, 0, v14
	v_max_f32_e32 v15, 0, v15
	v_max_f32_e32 v16, 0, v16
	v_max_f32_e32 v17, 0, v17
	v_max_f32_e32 v10, 0, v10
	v_max_f32_e32 v11, 0, v11
	v_max_f32_e32 v12, 0, v12
	v_max_f32_e32 v13, 0, v13
	v_pk_mul_f32 v[14:15], v[14:15], v[14:15]
	v_pk_mul_f32 v[16:17], v[16:17], v[16:17]
	v_pk_mul_f32 v[10:11], v[10:11], v[10:11]
	v_pk_mul_f32 v[12:13], v[12:13], v[12:13]
	v_cvt_pk_bf16_f32 v14, v14, v15
	v_cvt_pk_bf16_f32 v15, v16, v17
	v_cvt_pk_bf16_f32 v16, v10, v11
	v_cvt_pk_bf16_f32 v17, v12, v13
	buffer_store_dwordx4 v[14:17], v141, s[88:91], s100 offen sc1
	v_pk_mul_f32 v[6:7], v[6:7], v[254:255] op_sel_hi:[1,0]
	v_pk_mul_f32 v[8:9], v[8:9], v[254:255] op_sel_hi:[1,0]
	v_pk_mul_f32 v[2:3], v[2:3], v[254:255] op_sel_hi:[1,0]
	v_pk_mul_f32 v[4:5], v[4:5], v[254:255] op_sel_hi:[1,0]
	v_max_f32_e32 v6, 0, v6
	v_max_f32_e32 v7, 0, v7
	v_max_f32_e32 v8, 0, v8
	v_max_f32_e32 v9, 0, v9
	v_max_f32_e32 v2, 0, v2
	v_max_f32_e32 v3, 0, v3
	v_max_f32_e32 v4, 0, v4
	v_max_f32_e32 v5, 0, v5
	v_pk_mul_f32 v[6:7], v[6:7], v[6:7]
	v_pk_mul_f32 v[8:9], v[8:9], v[8:9]
	v_pk_mul_f32 v[2:3], v[2:3], v[2:3]
	v_pk_mul_f32 v[4:5], v[4:5], v[4:5]
	v_cvt_pk_bf16_f32 v6, v6, v7
	v_cvt_pk_bf16_f32 v7, v8, v9
	v_cvt_pk_bf16_f32 v8, v2, v3
	v_cvt_pk_bf16_f32 v9, v4, v5
	buffer_store_dwordx4 v[6:9], v141, s[88:91], s100 offen offset:256 sc1
	s_andn2_b64 vcc, exec, s[0:1]
	s_mov_b64 s[0:1], -1
	s_cbranch_vccnz .LBB0_1032
	s_andn2_b64 vcc, exec, s[4:5]
	s_cbranch_vccnz .LBB0_1031
	s_barrier
	s_branch .LBB0_1031

	.amdhsa_kernel _Z8yoco_fwd4Args
		.amdhsa_group_segment_fixed_size 0
		.amdhsa_private_segment_fixed_size 0
		.amdhsa_kernarg_size 632
		.amdhsa_user_sgpr_count 2
		.amdhsa_user_sgpr_dispatch_ptr 0
		.amdhsa_user_sgpr_queue_ptr 0
		.amdhsa_user_sgpr_kernarg_segment_ptr 1
		.amdhsa_user_sgpr_dispatch_id 0
		.amdhsa_user_sgpr_kernarg_preload_length 0
		.amdhsa_user_sgpr_kernarg_preload_offset 0
		.amdhsa_user_sgpr_private_segment_size 0
		.amdhsa_uses_dynamic_stack 0
		.amdhsa_enable_private_segment 0
		.amdhsa_system_sgpr_workgroup_id_x 1
		.amdhsa_system_sgpr_workgroup_id_y 0
		.amdhsa_system_sgpr_workgroup_id_z 0
		.amdhsa_system_sgpr_workgroup_info 0
		.amdhsa_system_vgpr_workitem_id 0
		.amdhsa_next_free_vgpr 256
		.amdhsa_next_free_sgpr 102
		.amdhsa_accum_offset 256
		.amdhsa_reserve_vcc 1
		.amdhsa_float_round_mode_32 0
		.amdhsa_float_round_mode_16_64 0
		.amdhsa_float_denorm_mode_32 3
		.amdhsa_float_denorm_mode_16_64 3
		.amdhsa_dx10_clamp 1
		.amdhsa_ieee_mode 1
		.amdhsa_fp16_overflow 0
		.amdhsa_tg_split 0
		.amdhsa_exception_fp_ieee_invalid_op 0
		.amdhsa_exception_fp_denorm_src 0
		.amdhsa_exception_fp_ieee_div_zero 0
		.amdhsa_exception_fp_ieee_overflow 0
		.amdhsa_exception_fp_ieee_underflow 0
		.amdhsa_exception_fp_ieee_inexact 0
		.amdhsa_exception_int_div_zero 0
	.end_amdhsa_kernel

amdhsa.kernels:
  - .agpr_count:     0
    .args:
      - .offset:         0
        .size:           376
        .value_kind:     by_value
      - .offset:         376
        .size:           4
        .value_kind:     hidden_block_count_x
      - .offset:         380
        .size:           4
        .value_kind:     hidden_block_count_y
      - .offset:         384
        .size:           4
        .value_kind:     hidden_block_count_z
      - .offset:         388
        .size:           2
        .value_kind:     hidden_group_size_x
      - .offset:         390
        .size:           2
        .value_kind:     hidden_group_size_y
      - .offset:         392
        .size:           2
        .value_kind:     hidden_group_size_z
      - .offset:         394
        .size:           2
        .value_kind:     hidden_remainder_x
      - .offset:         396
        .size:           2
        .value_kind:     hidden_remainder_y
      - .offset:         398
        .size:           2
        .value_kind:     hidden_remainder_z
      - .offset:         416
        .size:           8
        .value_kind:     hidden_global_offset_x
      - .offset:         424
        .size:           8
        .value_kind:     hidden_global_offset_y
      - .offset:         432
        .size:           8
        .value_kind:     hidden_global_offset_z
      - .offset:         440
        .size:           2
        .value_kind:     hidden_grid_dims
      - .offset:         496
        .size:           4
        .value_kind:     hidden_dynamic_lds_size
    .group_segment_fixed_size: 0
    .kernarg_segment_align: 8
    .kernarg_segment_size: 632
    .language:       OpenCL C
    .language_version:
      - 2
      - 0
    .max_flat_workgroup_size: 512
    .name:           _Z8yoco_fwd4Args
    .private_segment_fixed_size: 0
    .sgpr_count:     108
    .sgpr_spill_count: 25
    .symbol:         _Z8yoco_fwd4Args.kd
    .uniform_work_group_size: 1
    .uses_dynamic_stack: false
    .vgpr_count:     256
    .vgpr_spill_count: 0
    .wavefront_size: 64
